# ctx attention units shifted off the ctx-DFT workgroups; last two grid barriers use the hierarchical per-XCC barrier
# speedup vs baseline: 1.0613x; 1.0067x over previous
; __device__ __forceinline__ void attn_phase(const Params& p, int l, LAS unsigned char* lds, int tid) {
;     ...
;     for (int u = blockIdx.x; u < nunits; u += gridDim.x) {
;         const bool lat = u < 512;
;         const int v = lat ? u : u - 512;
;         const int b = lat ? (v >> 6) : (v >> 3), head = lat ? ((v >> 3) & 7) : (v & 7), qb = v & 7, kvh = head >> 2;
;         const size_t qrow = (size_t)(b * 8 + head) * TKV + (lat ? 256 + qb * 512 : 0);
;         const size_t orow = lat ? (size_t)(b * SEQ + qb * 512) : (size_t)(MX + b * CTX);
;         attn_unit(QS + qrow * 64, KS + (size_t)(b * 2 + kvh) * TKV * 64, VT + (size_t)(b * 2 + kvh) * 64 * TKV, lat ? TKV / 64 : CTX / 64, lat ? 512 : 256,
;                   MIX + orow * KOUT + head * 64, negM, lds, tid);
;     }
.LBB0_477:
	s_or_b64 exec, exec, s[4:5]
	s_mov_b32 s7, s101
	s_add_i32 s7, s7, s90
	s_cmpk_lt_i32 s7, 0x200
	s_cbranch_scc1 .Lattn_nx
	s_sub_i32 s7, s7, 8
	s_cmpk_lt_i32 s7, 0x200
	s_cbranch_scc1 .LBB0_491
.Lattn_nx:
	s_cmp_ge_i32 s7, s6
	s_cbranch_scc1 .LBB0_491

; __device__ __forceinline__ unsigned xb_ld(unsigned* p)              { return __hip_atomic_load(p, __ATOMIC_RELAXED, __HIP_MEMORY_SCOPE_AGENT); }
; __device__ __forceinline__ unsigned xb_add(unsigned* p, unsigned v) { return __hip_atomic_fetch_add(p, v, __ATOMIC_RELAXED, __HIP_MEMORY_SCOPE_AGENT); }
; __device__ __forceinline__ void xcd_barrier_complete(unsigned* bar, unsigned x, unsigned& nloc, unsigned& nx) {
;     ...
;     for (;;) {
;         sum = 0u; cnt = 0u; mine = 0u;
; #pragma unroll
;         for (unsigned j = 0; j < 16; ++j) { const unsigned c = xb_ld(&bar[XB_XCNT(j)]); sum += c; cnt += (c > 0u) ? 1u : 0u; mine = (j == x) ? c : mine; }
;         if (sum == G) break;
;         __builtin_amdgcn_s_sleep(1);
;         if ((++sp & 255u) == 0u) { if (xb_ld(&bar[XB_TMO])) break; if (sp > XB_SPIN_CAP) { atomicAdd(&bar[XB_TMO], 1u); break; } }
;     }
; __device__ __forceinline__ void xcd_barrier(const XcdBarrier& b) {
;     asm volatile("s_waitcnt vmcnt(0)" ::: "memory");
;     __syncthreads();
;     if (threadIdx.x == 0) {
;         unsigned* bar = b.bar;
;         __builtin_amdgcn_s_waitcnt(0);
;         unsigned nloc = b.st[0], nx = b.st[1];
;         if (nloc == 0u) { xcd_barrier_complete(bar, b.x, nloc, nx); b.st[0] = nloc; b.st[1] = nx; }
;         const unsigned old = xb_add(&bar[XB_XSUB(b.x)], 1u);
.LBB0_753:
	v_readlane_b32 s34, v253, 17
	v_readlane_b32 s92, v253, 22
	v_readlane_b32 s42, v253, 24
	v_readlane_b32 s48, v253, 49
	s_and_b64 vcc, s[64:65], exec
	v_readlane_b32 s28, v253, 15
	v_readlane_b32 s35, v253, 18
	v_readlane_b32 s40, v253, 19
	v_readlane_b32 s93, v253, 23
	v_readlane_b32 s43, v253, 25
	v_readlane_b32 s49, v253, 50
	v_readlane_b32 s29, v253, 16
	s_cbranch_vccz .LBB0_143
	s_waitcnt vmcnt(0)
	s_waitcnt vmcnt(0) lgkmcnt(0)
	s_barrier
	s_add_i32 s98, s98, 1
	s_mov_b64 s[0:1], exec
	v_readlane_b32 s4, v252, 0
	v_readlane_b32 s5, v252, 1
	s_and_b64 s[4:5], s[0:1], s[4:5]
	s_mov_b64 exec, s[4:5]
	s_cbranch_execz .LBB0_813
	s_add_u32 s10, s88, 0x9000
	s_addc_u32 s11, s89, 0
	s_cmp_lg_u32 s100, 0
	s_cbranch_scc1 .Lxb_have_u
	s_add_u32 s8, s88, 0x1400
	s_addc_u32 s9, s89, 0
.Lxb_census_u:
	v_mov_b32_e32 v0, 0
	global_load_dword v1, v0, s[8:9] sc1
	global_load_dword v2, v0, s[8:9] offset:256 sc1
	global_load_dword v3, v0, s[8:9] offset:512 sc1
	global_load_dword v4, v0, s[8:9] offset:768 sc1
	global_load_dword v5, v0, s[8:9] offset:1024 sc1
	global_load_dword v6, v0, s[8:9] offset:1280 sc1
	global_load_dword v7, v0, s[8:9] offset:1536 sc1
	global_load_dword v8, v0, s[8:9] offset:1792 sc1
	global_load_dword v9, v0, s[8:9] offset:2048 sc1
	global_load_dword v10, v0, s[8:9] offset:2304 sc1
	global_load_dword v11, v0, s[8:9] offset:2560 sc1
	global_load_dword v12, v0, s[8:9] offset:2816 sc1
	global_load_dword v13, v0, s[8:9] offset:3072 sc1
	global_load_dword v14, v0, s[8:9] offset:3328 sc1
	global_load_dword v15, v0, s[8:9] offset:3584 sc1
	global_load_dword v16, v0, s[8:9] offset:3840 sc1
	s_waitcnt vmcnt(0)
	v_add3_u32 v0, v1, v2, v3
	v_add3_u32 v0, v0, v4, v5
	v_add3_u32 v0, v0, v6, v7
	v_add3_u32 v0, v0, v8, v9
	v_add3_u32 v0, v0, v10, v11
	v_add3_u32 v0, v0, v12, v13
	v_add3_u32 v0, v0, v14, v15
	v_add_u32_e32 v0, v0, v16
	s_nop 0
	v_readfirstlane_b32 s4, v0
	s_nop 3
	s_cmp_eq_u32 s4, s90
	s_cbranch_scc1 .Lxb_cdone_u
	s_sleep 2
	s_branch .Lxb_census_u

; __device__ __forceinline__ unsigned xb_ld(unsigned* p)              { return __hip_atomic_load(p, __ATOMIC_RELAXED, __HIP_MEMORY_SCOPE_AGENT); }
; __device__ __forceinline__ unsigned xb_add(unsigned* p, unsigned v) { return __hip_atomic_fetch_add(p, v, __ATOMIC_RELAXED, __HIP_MEMORY_SCOPE_AGENT); }
; #define XB_SPIN(cond, bar) do { unsigned _sp = 0; while (cond) { __builtin_amdgcn_s_sleep(1); \
;     if ((++_sp & 255u) == 0u) { if (xb_ld(&(bar)[XB_TMO])) break; if (_sp > XB_SPIN_CAP) { atomicAdd(&(bar)[XB_TMO], 1u); break; } } } } while (0)
; __device__ __forceinline__ void xcd_barrier(const XcdBarrier& b) {
;     ...
;         const unsigned old = xb_add(&bar[XB_XSUB(b.x)], 1u);
;         const unsigned gen = old / nloc;
;         if (old + 1u == (gen + 1u) * nloc) {
;             __builtin_amdgcn_fence(__ATOMIC_RELEASE, "agent");
;             asm volatile("s_waitcnt vmcnt(0)" ::: "memory");
;             const unsigned og = xb_add(&bar[XB_TOP], 1u);
;             const unsigned tg = og / nx;
;             if (og + 1u == (tg + 1u) * nx) xb_add(&bar[XB_TOPGEN], 1u);
;             else XB_SPIN(xb_ld(&bar[XB_TOPGEN]) == tg, bar);
;             __builtin_amdgcn_fence(__ATOMIC_ACQUIRE, "agent");
;             xb_add(&bar[XB_XGEN(b.x)], 1u);
;             asm volatile("s_waitcnt vmcnt(0)" ::: "memory");
.Lxb_have_u:
	s_lshl_b32 s6, s99, 8
	v_mov_b32_e32 v0, s6
	v_mov_b32_e32 v1, 1
	global_atomic_add v2, v0, v1, s[10:11] sc0
	s_mul_i32 s7, s98, s100
	s_waitcnt vmcnt(0)
	v_readfirstlane_b32 s4, v2
	s_nop 3
	s_add_i32 s4, s4, 1
	s_cmp_lg_u32 s4, s7
	s_cbranch_scc1 .Lxb_poll_u
	buffer_wbl2 sc1
	s_waitcnt vmcnt(0)
	v_mov_b32_e32 v3, 0x1000
	v_mov_b32_e32 v4, s100
	global_atomic_add v2, v3, v4, s[10:11] sc0
	s_mul_i32 s7, s98, s90
	s_waitcnt vmcnt(0)
	v_readfirstlane_b32 s4, v2
	s_nop 3
	s_add_i32 s4, s4, s100
	s_cmp_lg_u32 s4, s7
	s_cbranch_scc1 .Lxb_poll_u
	v_mov_b32_e32 v3, 0
	v_mov_b32_e32 v4, s98
	s_add_u32 s8, s10, 0x1100
	s_addc_u32 s9, s11, 0
	global_store_dword v3, v4, s[8:9] sc0 sc1
	global_store_dword v3, v4, s[8:9] offset:256 sc0 sc1
	global_store_dword v3, v4, s[8:9] offset:512 sc0 sc1
	global_store_dword v3, v4, s[8:9] offset:768 sc0 sc1
	global_store_dword v3, v4, s[8:9] offset:1024 sc0 sc1
	global_store_dword v3, v4, s[8:9] offset:1280 sc0 sc1
	global_store_dword v3, v4, s[8:9] offset:1536 sc0 sc1
	global_store_dword v3, v4, s[8:9] offset:1792 sc0 sc1
	global_store_dword v3, v4, s[8:9] offset:2048 sc0 sc1
	global_store_dword v3, v4, s[8:9] offset:2304 sc0 sc1
	global_store_dword v3, v4, s[8:9] offset:2560 sc0 sc1
	global_store_dword v3, v4, s[8:9] offset:2816 sc0 sc1
	global_store_dword v3, v4, s[8:9] offset:3072 sc0 sc1
	global_store_dword v3, v4, s[8:9] offset:3328 sc0 sc1
	global_store_dword v3, v4, s[8:9] offset:3584 sc0 sc1
	global_store_dword v3, v4, s[8:9] offset:3840 sc0 sc1
	s_waitcnt vmcnt(0)

; __device__ __forceinline__ unsigned xb_ld(unsigned* p)              { return __hip_atomic_load(p, __ATOMIC_RELAXED, __HIP_MEMORY_SCOPE_AGENT); }
; #define XB_SPIN(cond, bar) do { unsigned _sp = 0; while (cond) { __builtin_amdgcn_s_sleep(1); \
;     if ((++_sp & 255u) == 0u) { if (xb_ld(&(bar)[XB_TMO])) break; if (_sp > XB_SPIN_CAP) { atomicAdd(&(bar)[XB_TMO], 1u); break; } } } } while (0)
; __device__ __forceinline__ void xcd_barrier(const XcdBarrier& b) {
;     ...
;             asm volatile("s_waitcnt vmcnt(0)" ::: "memory");
;         } else {
;             XB_SPIN(xb_ld(&bar[XB_XGEN(b.x)]) == gen, bar);
;             __builtin_amdgcn_fence(__ATOMIC_ACQUIRE, "agent");
;             asm volatile("s_waitcnt vmcnt(0)" ::: "memory");
;         }
;     }
;     __syncthreads();
.Lxb_done_u:
	s_waitcnt vmcnt(0)
	s_branch .LBB0_813

; #define PG8_STAGE(bufoff, gbase, voff) do { _Pragma("unroll") for (int _i = 0; _i < 2; ++_i) \
;         __builtin_amdgcn_global_load_lds((const unsigned*)((const char*)(gbase) + (voff)[_i]), (PG8_LAS unsigned*)(lds + (bufoff) + ldsw + _i * 8192), 16, 0, 0); } while (0)
; #define PG8_LDA(dst, b, h) do { _Pragma("unroll") for (int m = 0; m < 4; ++m) _Pragma("unroll") for (int k = 0; k < 2; ++k) dst[m][k] = *(const PG8_LAS bf16x8*)(lds + PG8_SA(b, h) + aoff + m * 2048 + k * 1024); } while (0)
; #define PG8_LDB(dst, b, h) do { _Pragma("unroll") for (int n = 0; n < 2; ++n) _Pragma("unroll") for (int k = 0; k < 2; ++k) dst[n][k] = *(const PG8_LAS bf16x8*)(lds + PG8_SB(b, h) + boff + n * 2048 + k * 1024); } while (0)
; #define PG8_MMA(ai, bj, At, Bt) do { __builtin_amdgcn_s_setprio(1); _Pragma("unroll") for (int m = 0; m < 4; ++m) _Pragma("unroll") for (int n = 0; n < 2; ++n) _Pragma("unroll") for (int k = 0; k < 2; ++k) \
;         acc[ai][bj][m][n] = __builtin_amdgcn_mfma_f32_16x16x32_bf16(Bt[n][k], At[m][k], acc[ai][bj][m][n], 0, 0, 0); __builtin_amdgcn_s_setprio(0); } while (0)
; #define PG8_WAIT_V(n) asm volatile("s_waitcnt vmcnt(" #n ")" ::: "memory")
; #define PG8_WAIT_L(n) asm volatile("s_waitcnt lgkmcnt(" #n ")" ::: "memory")
; #define PG8_BAR __builtin_amdgcn_s_barrier()
; #define PG8_SCHED __builtin_amdgcn_sched_barrier(0)
; template <class Epi, class Sched, bool ALIGN_EPI = false, bool SP2 = false>
; __device__ __forceinline__ void gemm_phase(PG8_LAS unsigned char* lds, const Gemm g, const Sched& S, const Epi& E) {
;     ...
;             PG8_LDB(B0, 0, 0); PG8_LDB(B1, 0, 1); PG8_SCHED; PG8_LDA(At, 0, 0); PG8_STAGE(PG8_SA(1, 1), a1 + hstep, voffA);
;             PG8_WAIT_V(8); PG8_WAIT_L(0); PG8_BAR; PG8_MMA(0, 0, At, B0); PG8_MMA(0, 1, At, B1); PG8_BAR; PG8_SCHED;
;             PG8_LDA(At, 0, 1); PG8_STAGE(PG8_SB(0, 0), b2, voffB); PG8_STAGE(PG8_SB(0, 1), b2 + hstep, voffB); PG8_STAGE(PG8_SA(0, 0), a2, voffA);
.LBB0_761:
	s_add_u32 s10, s48, s8
	s_addc_u32 s11, s49, s9
	s_add_u32 s10, s10, 0x1c000100
	s_addc_u32 s11, s11, 0
	s_add_u32 s53, s41, s8
	s_addc_u32 s54, s43, s9
	s_add_i32 s55, 0, 0x10000
	s_cmpk_eq_i32 s8, 0x700
	s_cselect_b32 s13, s7, s11
	s_cselect_b32 s12, s6, s10
	v_add_u32_e32 v142, s55, v136
	s_cselect_b32 s11, s5, s54
	s_cselect_b32 s10, s4, s53
	s_add_i32 s53, 0, 0x14000
	ds_read_b128 v[138:141], v142
	ds_read_b128 v[146:149], v142 offset:1024
	ds_read_b128 v[150:153], v142 offset:2048
	ds_read_b128 v[154:157], v142 offset:3072
	v_add_u32_e32 v142, s53, v136
	ds_read_b128 v[158:161], v142
	ds_read_b128 v[162:165], v142 offset:1024
	ds_read_b128 v[166:169], v142 offset:2048
	ds_read_b128 v[170:173], v142 offset:3072
	v_lshl_add_u64 v[142:143], v[130:131], 0, s[8:9]
	s_add_i32 m0, s37, 0xc000
	ds_read_b128 v[174:177], v137
	ds_read_b128 v[178:181], v137 offset:1024
	ds_read_b128 v[182:185], v137 offset:2048
	ds_read_b128 v[192:195], v137 offset:3072
	ds_read_b128 v[196:199], v137 offset:4096
	ds_read_b128 v[200:203], v137 offset:5120
	ds_read_b128 v[204:207], v137 offset:6144
	ds_read_b128 v[208:211], v137 offset:7168
	global_load_lds_dwordx4 v[142:143], off
	v_lshl_add_u64 v[142:143], v[132:133], 0, s[8:9]
	s_add_i32 m0, s37, 0xe000
	s_nop 0
	global_load_lds_dwordx4 v[142:143], off
	s_waitcnt vmcnt(8)
	s_waitcnt lgkmcnt(0)
	s_barrier
	s_setprio 1
	s_waitcnt lgkmcnt(0)
	v_mfma_f32_16x16x32_bf16 v[124:127], v[138:141], v[174:177], v[124:127]
	v_mfma_f32_16x16x32_bf16 v[120:123], v[150:153], v[174:177], v[120:123]
	v_mfma_f32_16x16x32_bf16 v[116:119], v[138:141], v[182:185], v[116:119]
	v_mfma_f32_16x16x32_bf16 v[112:115], v[150:153], v[182:185], v[112:115]
	v_mfma_f32_16x16x32_bf16 v[108:111], v[138:141], v[196:199], v[108:111]
	v_mfma_f32_16x16x32_bf16 v[100:103], v[150:153], v[196:199], v[100:103]
	v_mfma_f32_16x16x32_bf16 v[92:95], v[138:141], v[204:207], v[92:95]
	v_mfma_f32_16x16x32_bf16 v[84:87], v[150:153], v[204:207], v[84:87]
	v_mfma_f32_16x16x32_bf16 v[124:127], v[146:149], v[178:181], v[124:127]
	v_mfma_f32_16x16x32_bf16 v[120:123], v[154:157], v[178:181], v[120:123]
	v_mfma_f32_16x16x32_bf16 v[116:119], v[146:149], v[192:195], v[116:119]
	v_mfma_f32_16x16x32_bf16 v[112:115], v[154:157], v[192:195], v[112:115]
	v_mfma_f32_16x16x32_bf16 v[108:111], v[146:149], v[200:203], v[108:111]
	v_mfma_f32_16x16x32_bf16 v[100:103], v[154:157], v[200:203], v[100:103]
	v_mfma_f32_16x16x32_bf16 v[92:95], v[146:149], v[208:211], v[92:95]
	v_mfma_f32_16x16x32_bf16 v[84:87], v[154:157], v[208:211], v[84:87]
	s_setprio 0
	s_setprio 1
	v_mfma_f32_16x16x32_bf16 v[104:107], v[158:161], v[174:177], v[104:107]
	v_mfma_f32_16x16x32_bf16 v[96:99], v[166:169], v[174:177], v[96:99]
	v_mfma_f32_16x16x32_bf16 v[88:91], v[158:161], v[182:185], v[88:91]
	v_mfma_f32_16x16x32_bf16 v[80:83], v[166:169], v[182:185], v[80:83]
	v_mfma_f32_16x16x32_bf16 v[76:79], v[158:161], v[196:199], v[76:79]
	v_mfma_f32_16x16x32_bf16 v[72:75], v[166:169], v[196:199], v[72:75]
	v_mfma_f32_16x16x32_bf16 v[68:71], v[158:161], v[204:207], v[68:71]
	v_mfma_f32_16x16x32_bf16 v[64:67], v[166:169], v[204:207], v[64:67]
	v_mfma_f32_16x16x32_bf16 v[104:107], v[162:165], v[178:181], v[104:107]
	v_mfma_f32_16x16x32_bf16 v[96:99], v[170:173], v[178:181], v[96:99]
	v_mfma_f32_16x16x32_bf16 v[88:91], v[162:165], v[192:195], v[88:91]
	v_mfma_f32_16x16x32_bf16 v[80:83], v[170:173], v[192:195], v[80:83]
	v_mfma_f32_16x16x32_bf16 v[76:79], v[162:165], v[200:203], v[76:79]
	v_mfma_f32_16x16x32_bf16 v[72:75], v[170:173], v[200:203], v[72:75]
	v_mfma_f32_16x16x32_bf16 v[68:71], v[162:165], v[208:211], v[68:71]
	v_mfma_f32_16x16x32_bf16 v[64:67], v[170:173], v[208:211], v[64:67]
	s_setprio 0
	s_barrier
	s_add_i32 s54, s55, s36
	v_lshl_add_u64 v[142:143], s[10:11], 0, v[186:187]
	s_mov_b32 m0, s54
	ds_read_b128 v[174:177], v137 offset:16384
	ds_read_b128 v[178:181], v137 offset:17408
	ds_read_b128 v[182:185], v137 offset:18432
	ds_read_b128 v[192:195], v137 offset:19456
	ds_read_b128 v[196:199], v137 offset:20480
	ds_read_b128 v[200:203], v137 offset:21504
	ds_read_b128 v[204:207], v137 offset:22528
	ds_read_b128 v[208:211], v137 offset:23552
	global_load_lds_dwordx4 v[142:143], off
	s_add_i32 m0, s54, 0x2000
	s_add_u32 s54, s10, 0x100000
	v_lshl_add_u64 v[188:189], s[10:11], 0, v[128:129]
	s_addc_u32 s55, s11, 0
	s_add_i32 s53, s53, s36
	global_load_lds_dwordx4 v[188:189], off
	v_lshl_add_u64 v[212:213], s[54:55], 0, v[186:187]
	s_mov_b32 m0, s53
	v_lshl_add_u64 v[214:215], s[12:13], 0, v[128:129]
	global_load_lds_dwordx4 v[212:213], off
	v_lshl_add_u64 v[212:213], s[54:55], 0, v[128:129]
	s_add_i32 m0, s53, 0x2000
	s_nop 0
	global_load_lds_dwordx4 v[212:213], off
	v_lshl_add_u64 v[212:213], s[12:13], 0, v[186:187]
	s_mov_b32 m0, s37
	s_nop 0
	global_load_lds_dwordx4 v[212:213], off
	s_mov_b32 m0, s38
	s_nop 0
	global_load_lds_dwordx4 v[214:215], off
	s_waitcnt vmcnt(8)
	s_waitcnt lgkmcnt(0)
	s_barrier
; #define PG8_STAGE(bufoff, gbase, voff) do { _Pragma("unroll") for (int _i = 0; _i < 2; ++_i) \
;         __builtin_amdgcn_global_load_lds((const unsigned*)((const char*)(gbase) + (voff)[_i]), (PG8_LAS unsigned*)(lds + (bufoff) + ldsw + _i * 8192), 16, 0, 0); } while (0)
; #define PG8_LDA(dst, b, h) do { _Pragma("unroll") for (int m = 0; m < 4; ++m) _Pragma("unroll") for (int k = 0; k < 2; ++k) dst[m][k] = *(const PG8_LAS bf16x8*)(lds + PG8_SA(b, h) + aoff + m * 2048 + k * 1024); } while (0)
; #define PG8_LDB(dst, b, h) do { _Pragma("unroll") for (int n = 0; n < 2; ++n) _Pragma("unroll") for (int k = 0; k < 2; ++k) dst[n][k] = *(const PG8_LAS bf16x8*)(lds + PG8_SB(b, h) + boff + n * 2048 + k * 1024); } while (0)
; #define PG8_MMA(ai, bj, At, Bt) do { __builtin_amdgcn_s_setprio(1); _Pragma("unroll") for (int m = 0; m < 4; ++m) _Pragma("unroll") for (int n = 0; n < 2; ++n) _Pragma("unroll") for (int k = 0; k < 2; ++k) \
;         acc[ai][bj][m][n] = __builtin_amdgcn_mfma_f32_16x16x32_bf16(Bt[n][k], At[m][k], acc[ai][bj][m][n], 0, 0, 0); __builtin_amdgcn_s_setprio(0); } while (0)
; #define PG8_WAIT_V(n) asm volatile("s_waitcnt vmcnt(" #n ")" ::: "memory")
; #define PG8_WAIT_L(n) asm volatile("s_waitcnt lgkmcnt(" #n ")" ::: "memory")
; #define PG8_BAR __builtin_amdgcn_s_barrier()
; #define PG8_SCHED __builtin_amdgcn_sched_barrier(0)
; template <class Epi, class Sched, bool ALIGN_EPI = false, bool SP2 = false>
; __device__ __forceinline__ void gemm_phase(PG8_LAS unsigned char* lds, const Gemm g, const Sched& S, const Epi& E) {
;     ...
;             PG8_WAIT_V(8); PG8_WAIT_L(0); PG8_BAR; PG8_MMA(1, 0, At, B0); PG8_MMA(1, 1, At, B1); PG8_BAR; PG8_SCHED;
;             PG8_LDB(B0, 1, 0); PG8_LDB(B1, 1, 1); PG8_SCHED; PG8_LDA(At, 1, 0); PG8_STAGE(PG8_SA(0, 1), a2 + hstep, voffA);
;             PG8_WAIT_V(8); PG8_WAIT_L(0); PG8_BAR; PG8_MMA(0, 0, At, B0); PG8_MMA(0, 1, At, B1); PG8_BAR; PG8_SCHED;
	s_setprio 1
	s_waitcnt lgkmcnt(0)
	v_mfma_f32_16x16x32_bf16 v[60:63], v[138:141], v[174:177], v[60:63]
	v_mfma_f32_16x16x32_bf16 v[56:59], v[150:153], v[174:177], v[56:59]
	v_mfma_f32_16x16x32_bf16 v[52:55], v[138:141], v[182:185], v[52:55]
	v_mfma_f32_16x16x32_bf16 v[48:51], v[150:153], v[182:185], v[48:51]
	v_mfma_f32_16x16x32_bf16 v[44:47], v[138:141], v[196:199], v[44:47]
	v_mfma_f32_16x16x32_bf16 v[40:43], v[150:153], v[196:199], v[40:43]
	v_mfma_f32_16x16x32_bf16 v[32:35], v[138:141], v[204:207], v[32:35]
	v_mfma_f32_16x16x32_bf16 v[24:27], v[150:153], v[204:207], v[24:27]
	v_mfma_f32_16x16x32_bf16 v[60:63], v[146:149], v[178:181], v[60:63]
	v_mfma_f32_16x16x32_bf16 v[56:59], v[154:157], v[178:181], v[56:59]
	v_mfma_f32_16x16x32_bf16 v[52:55], v[146:149], v[192:195], v[52:55]
	v_mfma_f32_16x16x32_bf16 v[48:51], v[154:157], v[192:195], v[48:51]
	v_mfma_f32_16x16x32_bf16 v[44:47], v[146:149], v[200:203], v[44:47]
	v_mfma_f32_16x16x32_bf16 v[40:43], v[154:157], v[200:203], v[40:43]
	v_mfma_f32_16x16x32_bf16 v[32:35], v[146:149], v[208:211], v[32:35]
	v_mfma_f32_16x16x32_bf16 v[24:27], v[154:157], v[208:211], v[24:27]
	s_setprio 0
	s_setprio 1
	v_mfma_f32_16x16x32_bf16 v[36:39], v[158:161], v[174:177], v[36:39]
	v_mfma_f32_16x16x32_bf16 v[28:31], v[166:169], v[174:177], v[28:31]
	v_mfma_f32_16x16x32_bf16 v[20:23], v[158:161], v[182:185], v[20:23]
	v_mfma_f32_16x16x32_bf16 v[16:19], v[166:169], v[182:185], v[16:19]
	v_mfma_f32_16x16x32_bf16 v[12:15], v[158:161], v[196:199], v[12:15]
	v_mfma_f32_16x16x32_bf16 v[8:11], v[166:169], v[196:199], v[8:11]
	v_mfma_f32_16x16x32_bf16 v[4:7], v[158:161], v[204:207], v[4:7]
	v_mfma_f32_16x16x32_bf16 v[0:3], v[166:169], v[204:207], v[0:3]
	v_mfma_f32_16x16x32_bf16 v[36:39], v[162:165], v[178:181], v[36:39]
	v_mfma_f32_16x16x32_bf16 v[28:31], v[170:173], v[178:181], v[28:31]
	v_mfma_f32_16x16x32_bf16 v[20:23], v[162:165], v[192:195], v[20:23]
	v_mfma_f32_16x16x32_bf16 v[16:19], v[170:173], v[192:195], v[16:19]
	v_mfma_f32_16x16x32_bf16 v[12:15], v[162:165], v[200:203], v[12:15]
	v_mfma_f32_16x16x32_bf16 v[8:11], v[170:173], v[200:203], v[8:11]
	v_mfma_f32_16x16x32_bf16 v[4:7], v[162:165], v[208:211], v[4:7]
	v_mfma_f32_16x16x32_bf16 v[0:3], v[170:173], v[208:211], v[0:3]
	s_setprio 0
	s_barrier
	s_add_i32 s53, 0, 0x18000
	v_add_u32_e32 v145, s53, v136
	s_add_i32 s54, 0, 0x1c000
	ds_read_b128 v[138:141], v145
	ds_read_b128 v[146:149], v145 offset:1024
	ds_read_b128 v[150:153], v145 offset:2048
	ds_read_b128 v[154:157], v145 offset:3072
	v_add_u32_e32 v145, s54, v136
	ds_read_b128 v[158:161], v145
	ds_read_b128 v[162:165], v145 offset:1024
	ds_read_b128 v[166:169], v145 offset:2048
	ds_read_b128 v[170:173], v145 offset:3072
	s_add_u32 s12, s12, 0x100000
	s_addc_u32 s13, s13, 0
	s_mov_b32 m0, s39
	v_lshl_add_u64 v[216:217], s[12:13], 0, v[186:187]
	ds_read_b128 v[174:177], v137 offset:32768
	ds_read_b128 v[178:181], v137 offset:33792
	ds_read_b128 v[182:185], v137 offset:34816
	ds_read_b128 v[192:195], v137 offset:35840
	ds_read_b128 v[196:199], v137 offset:36864
	ds_read_b128 v[200:203], v137 offset:37888
	ds_read_b128 v[204:207], v137 offset:38912
	ds_read_b128 v[208:211], v137 offset:39936
	global_load_lds_dwordx4 v[216:217], off
	v_lshl_add_u64 v[216:217], s[12:13], 0, v[128:129]
	s_mov_b32 m0, s40
	s_nop 0
	global_load_lds_dwordx4 v[216:217], off
	s_waitcnt vmcnt(8)
	s_waitcnt lgkmcnt(0)
	s_barrier
	s_setprio 1
	s_waitcnt lgkmcnt(0)
	v_mfma_f32_16x16x32_bf16 v[124:127], v[138:141], v[174:177], v[124:127]
	v_mfma_f32_16x16x32_bf16 v[120:123], v[150:153], v[174:177], v[120:123]
	v_mfma_f32_16x16x32_bf16 v[116:119], v[138:141], v[182:185], v[116:119]
	v_mfma_f32_16x16x32_bf16 v[112:115], v[150:153], v[182:185], v[112:115]
	v_mfma_f32_16x16x32_bf16 v[108:111], v[138:141], v[196:199], v[108:111]
	v_mfma_f32_16x16x32_bf16 v[100:103], v[150:153], v[196:199], v[100:103]
	v_mfma_f32_16x16x32_bf16 v[92:95], v[138:141], v[204:207], v[92:95]
	v_mfma_f32_16x16x32_bf16 v[84:87], v[150:153], v[204:207], v[84:87]
	v_mfma_f32_16x16x32_bf16 v[124:127], v[146:149], v[178:181], v[124:127]
	v_mfma_f32_16x16x32_bf16 v[120:123], v[154:157], v[178:181], v[120:123]
	v_mfma_f32_16x16x32_bf16 v[116:119], v[146:149], v[192:195], v[116:119]
	v_mfma_f32_16x16x32_bf16 v[112:115], v[154:157], v[192:195], v[112:115]
	v_mfma_f32_16x16x32_bf16 v[108:111], v[146:149], v[200:203], v[108:111]
	v_mfma_f32_16x16x32_bf16 v[100:103], v[154:157], v[200:203], v[100:103]
	v_mfma_f32_16x16x32_bf16 v[92:95], v[146:149], v[208:211], v[92:95]
	v_mfma_f32_16x16x32_bf16 v[84:87], v[154:157], v[208:211], v[84:87]
	s_setprio 0
	s_setprio 1
	v_mfma_f32_16x16x32_bf16 v[104:107], v[158:161], v[174:177], v[104:107]
	v_mfma_f32_16x16x32_bf16 v[96:99], v[166:169], v[174:177], v[96:99]
	v_mfma_f32_16x16x32_bf16 v[88:91], v[158:161], v[182:185], v[88:91]
	v_mfma_f32_16x16x32_bf16 v[80:83], v[166:169], v[182:185], v[80:83]
	v_mfma_f32_16x16x32_bf16 v[76:79], v[158:161], v[196:199], v[76:79]
	v_mfma_f32_16x16x32_bf16 v[72:75], v[166:169], v[196:199], v[72:75]
	v_mfma_f32_16x16x32_bf16 v[68:71], v[158:161], v[204:207], v[68:71]
	v_mfma_f32_16x16x32_bf16 v[64:67], v[166:169], v[204:207], v[64:67]
	v_mfma_f32_16x16x32_bf16 v[104:107], v[162:165], v[178:181], v[104:107]
	v_mfma_f32_16x16x32_bf16 v[96:99], v[170:173], v[178:181], v[96:99]
	v_mfma_f32_16x16x32_bf16 v[88:91], v[162:165], v[192:195], v[88:91]
	v_mfma_f32_16x16x32_bf16 v[80:83], v[170:173], v[192:195], v[80:83]
	v_mfma_f32_16x16x32_bf16 v[76:79], v[162:165], v[200:203], v[76:79]
	v_mfma_f32_16x16x32_bf16 v[72:75], v[170:173], v[200:203], v[72:75]
	v_mfma_f32_16x16x32_bf16 v[68:71], v[162:165], v[208:211], v[68:71]
	v_mfma_f32_16x16x32_bf16 v[64:67], v[170:173], v[208:211], v[64:67]
	s_setprio 0
	s_barrier
; #define PG8_STAGE(bufoff, gbase, voff) do { _Pragma("unroll") for (int _i = 0; _i < 2; ++_i) \
;         __builtin_amdgcn_global_load_lds((const unsigned*)((const char*)(gbase) + (voff)[_i]), (PG8_LAS unsigned*)(lds + (bufoff) + ldsw + _i * 8192), 16, 0, 0); } while (0)
; #define PG8_LDA(dst, b, h) do { _Pragma("unroll") for (int m = 0; m < 4; ++m) _Pragma("unroll") for (int k = 0; k < 2; ++k) dst[m][k] = *(const PG8_LAS bf16x8*)(lds + PG8_SA(b, h) + aoff + m * 2048 + k * 1024); } while (0)
; #define PG8_MMA(ai, bj, At, Bt) do { __builtin_amdgcn_s_setprio(1); _Pragma("unroll") for (int m = 0; m < 4; ++m) _Pragma("unroll") for (int n = 0; n < 2; ++n) _Pragma("unroll") for (int k = 0; k < 2; ++k) \
;         acc[ai][bj][m][n] = __builtin_amdgcn_mfma_f32_16x16x32_bf16(Bt[n][k], At[m][k], acc[ai][bj][m][n], 0, 0, 0); __builtin_amdgcn_s_setprio(0); } while (0)
; #define PG8_WAIT_V(n) asm volatile("s_waitcnt vmcnt(" #n ")" ::: "memory")
; #define PG8_WAIT_L(n) asm volatile("s_waitcnt lgkmcnt(" #n ")" ::: "memory")
; #define PG8_BAR __builtin_amdgcn_s_barrier()
; #define PG8_SCHED __builtin_amdgcn_sched_barrier(0)
; template <class Epi, class Sched, bool ALIGN_EPI = false, bool SP2 = false>
; __device__ __forceinline__ void gemm_phase(PG8_LAS unsigned char* lds, const Gemm g, const Sched& S, const Epi& E) {
;     ...
;             PG8_LDA(At, 1, 1); PG8_STAGE(PG8_SB(1, 0), b3, voffB); PG8_STAGE(PG8_SB(1, 1), b3 + hstep, voffB); PG8_STAGE(PG8_SA(1, 0), a3, voffA);
;             PG8_WAIT_V(8); PG8_WAIT_L(0); PG8_BAR; PG8_MMA(1, 0, At, B0); PG8_MMA(1, 1, At, B1); PG8_BAR; PG8_SCHED;
; __device__ __forceinline__ void ctx_finish_phase(const Params& p, int tid) {
;     unsigned char* ws = p.ws;
;     const int lane = tid & 63, wave = tid >> 6;
;     float* XC = (float*)(ws + WS_XC); const float* SL = (const float*)(ws + WS_SLAB);
;     const float* gate = (const float*)(ws + WS_MOD) + (size_t)8 * 6144 + 5 * 1024;
;     const float* gs = (const float*)(ws + WS_GS) + (size_t)(2 * 9 + 8) * 1024;
;     bf16_t* A1 = (bf16_t*)(ws + WS_A1); float* RS1 = (float*)(ws + WS_RS) + MT;
;     for (int row = blockIdx.x * 8 + wave; row < MC; row += gridDim.x * 8) {
;         float ss = 0.f;
; #pragma unroll
;         for (int j = 0; j < 4; ++j) {
;             const int col = 4 * lane + 256 * j; const size_t o = (size_t)row * DM + col;
	s_add_i32 s12, s53, s36
	v_lshl_add_u64 v[142:143], v[142:143], 0, s[44:45]
	s_mov_b32 m0, s12
	ds_read_b128 v[174:177], v137 offset:49152
	ds_read_b128 v[178:181], v137 offset:50176
	ds_read_b128 v[182:185], v137 offset:51200
	ds_read_b128 v[192:195], v137 offset:52224
	ds_read_b128 v[196:199], v137 offset:53248
	ds_read_b128 v[200:203], v137 offset:54272
	ds_read_b128 v[204:207], v137 offset:55296
	ds_read_b128 v[208:211], v137 offset:56320
	global_load_lds_dwordx4 v[142:143], off
	s_add_i32 m0, s12, 0x2000
	s_add_u32 s10, s10, 0x100080
	v_lshl_add_u64 v[142:143], v[188:189], 0, s[44:45]
	s_addc_u32 s11, s11, 0
	s_add_i32 s12, s54, s36
	global_load_lds_dwordx4 v[142:143], off
	v_lshl_add_u64 v[142:143], s[10:11], 0, v[186:187]
	s_mov_b32 m0, s12
	s_nop 0
	global_load_lds_dwordx4 v[142:143], off
	v_lshl_add_u64 v[142:143], s[10:11], 0, v[128:129]
	s_add_i32 m0, s12, 0x2000
	s_nop 0
	global_load_lds_dwordx4 v[142:143], off
	v_lshl_add_u64 v[142:143], v[212:213], 0, s[44:45]
	s_mov_b32 m0, s46
	s_nop 0
	global_load_lds_dwordx4 v[142:143], off
	v_lshl_add_u64 v[142:143], v[214:215], 0, s[44:45]
	s_mov_b32 m0, s47
	s_nop 0
	global_load_lds_dwordx4 v[142:143], off
	s_waitcnt vmcnt(8)
	s_waitcnt lgkmcnt(0)
	s_barrier
	s_setprio 1
	s_waitcnt lgkmcnt(0)
	v_mfma_f32_16x16x32_bf16 v[60:63], v[138:141], v[174:177], v[60:63]
	v_mfma_f32_16x16x32_bf16 v[56:59], v[150:153], v[174:177], v[56:59]
	v_mfma_f32_16x16x32_bf16 v[52:55], v[138:141], v[182:185], v[52:55]
	v_mfma_f32_16x16x32_bf16 v[48:51], v[150:153], v[182:185], v[48:51]
	v_mfma_f32_16x16x32_bf16 v[44:47], v[138:141], v[196:199], v[44:47]
	v_mfma_f32_16x16x32_bf16 v[40:43], v[150:153], v[196:199], v[40:43]
	v_mfma_f32_16x16x32_bf16 v[32:35], v[138:141], v[204:207], v[32:35]
	v_mfma_f32_16x16x32_bf16 v[24:27], v[150:153], v[204:207], v[24:27]
	v_mfma_f32_16x16x32_bf16 v[60:63], v[146:149], v[178:181], v[60:63]
	v_mfma_f32_16x16x32_bf16 v[56:59], v[154:157], v[178:181], v[56:59]
	v_mfma_f32_16x16x32_bf16 v[52:55], v[146:149], v[192:195], v[52:55]
	v_mfma_f32_16x16x32_bf16 v[48:51], v[154:157], v[192:195], v[48:51]
	v_mfma_f32_16x16x32_bf16 v[44:47], v[146:149], v[200:203], v[44:47]
	v_mfma_f32_16x16x32_bf16 v[40:43], v[154:157], v[200:203], v[40:43]
	v_mfma_f32_16x16x32_bf16 v[32:35], v[146:149], v[208:211], v[32:35]
	v_mfma_f32_16x16x32_bf16 v[24:27], v[154:157], v[208:211], v[24:27]
	s_setprio 0
	s_setprio 1
	v_mfma_f32_16x16x32_bf16 v[36:39], v[158:161], v[174:177], v[36:39]
	v_mfma_f32_16x16x32_bf16 v[28:31], v[166:169], v[174:177], v[28:31]
	v_mfma_f32_16x16x32_bf16 v[20:23], v[158:161], v[182:185], v[20:23]
	v_mfma_f32_16x16x32_bf16 v[16:19], v[166:169], v[182:185], v[16:19]
	v_mfma_f32_16x16x32_bf16 v[12:15], v[158:161], v[196:199], v[12:15]
	v_mfma_f32_16x16x32_bf16 v[8:11], v[166:169], v[196:199], v[8:11]
	v_mfma_f32_16x16x32_bf16 v[4:7], v[158:161], v[204:207], v[4:7]
	v_mfma_f32_16x16x32_bf16 v[0:3], v[166:169], v[204:207], v[0:3]
	v_mfma_f32_16x16x32_bf16 v[36:39], v[162:165], v[178:181], v[36:39]
	v_mfma_f32_16x16x32_bf16 v[28:31], v[170:173], v[178:181], v[28:31]
	v_mfma_f32_16x16x32_bf16 v[20:23], v[162:165], v[192:195], v[20:23]
	v_mfma_f32_16x16x32_bf16 v[16:19], v[170:173], v[192:195], v[16:19]
	v_mfma_f32_16x16x32_bf16 v[12:15], v[162:165], v[200:203], v[12:15]
	v_mfma_f32_16x16x32_bf16 v[8:11], v[170:173], v[200:203], v[8:11]
	v_mfma_f32_16x16x32_bf16 v[4:7], v[162:165], v[208:211], v[4:7]
	v_mfma_f32_16x16x32_bf16 v[0:3], v[170:173], v[208:211], v[0:3]
	s_setprio 0
	s_barrier
	s_add_i32 s52, s52, 2
	s_add_u32 s8, s8, 0x100
	s_addc_u32 s9, s9, 0
	s_cmp_gt_u32 s52, 13
	s_cbranch_scc0 .LBB0_761
	s_cmpk_lt_u32 s35, 0x100
	s_movk_i32 s46, 0x4000
	s_cbranch_scc0 .LBB0_757
	s_barrier
	s_branch .LBB0_757
.LBB0_813:
	s_or_b64 exec, exec, s[0:1]
	s_waitcnt lgkmcnt(0)
	s_barrier
	v_readlane_b32 s0, v252, 29
	v_ashrrev_i32_e32 v0, 6, v144
	s_nop 0
	v_add_u32_e32 v0, s0, v0
	s_movk_i32 s0, 0x800
	v_cmp_gt_i32_e32 vcc, s0, v0
	s_and_saveexec_b64 s[0:1], vcc
	s_xor_b64 s[4:5], exec, s[0:1]
	s_cbranch_execz .LBB0_819
	v_xor_b32_e32 v3, 1, v223
	v_cmp_lt_i32_e32 vcc, v3, v224
	v_and_b32_e32 v1, 63, v144
	v_lshlrev_b32_e32 v2, 2, v1
	v_cndmask_b32_e32 v3, v223, v3, vcc
	v_cmp_lt_i32_e32 vcc, v228, v224
	v_readlane_b32 s8, v255, 15
	v_readlane_b32 s6, v255, 13
	v_cndmask_b32_e32 v4, v223, v228, vcc
	v_cmp_lt_i32_e32 vcc, v225, v224
	v_lshlrev_b32_e32 v9, 2, v4
	v_lshlrev_b32_e32 v186, 4, v1
	v_cndmask_b32_e32 v4, v223, v225, vcc
	v_lshlrev_b32_e32 v15, 2, v4
	v_xor_b32_e32 v4, 8, v223
	v_cmp_lt_i32_e32 vcc, v4, v224
	v_readlane_b32 s9, v255, 16
	v_readlane_b32 s7, v255, 14
	v_cndmask_b32_e32 v4, v223, v4, vcc
	v_cmp_lt_i32_e32 vcc, v229, v224
	v_lshlrev_b32_e32 v21, 2, v4
	v_or_b32_e32 v8, 0x100, v2
	v_cndmask_b32_e32 v4, v223, v229, vcc
	v_cmp_lt_i32_e32 vcc, v230, v224
	v_lshlrev_b32_e32 v32, 2, v4
	v_lshl_add_u64 v[6:7], s[6:7], 0, v[186:187]
	v_cndmask_b32_e32 v4, v223, v230, vcc
	v_lshlrev_b32_e32 v33, 2, v4
	v_lshl_add_u64 v[4:5], s[8:9], 0, v[186:187]
	v_lshlrev_b32_e32 v186, 2, v8
	v_or_b32_e32 v14, 0x200, v2
	v_lshl_add_u64 v[10:11], s[8:9], 0, v[186:187]
	v_lshl_add_u64 v[12:13], s[6:7], 0, v[186:187]
	v_lshlrev_b32_e32 v186, 2, v14
	v_or_b32_e32 v20, 0x300, v2
	v_lshl_add_u64 v[16:17], s[8:9], 0, v[186:187]
	v_lshl_add_u64 v[18:19], s[6:7], 0, v[186:187]
	v_lshlrev_b32_e32 v186, 2, v20
	v_lshl_add_u64 v[24:25], s[6:7], 0, v[186:187]
	v_readlane_b32 s6, v255, 24
	v_lshl_add_u64 v[22:23], s[8:9], 0, v[186:187]
	v_lshlrev_b32_e32 v186, 3, v1
	v_readlane_b32 s7, v255, 25
	v_lshlrev_b32_e32 v3, 2, v3
	v_cmp_eq_u32_e64 s[0:1], 0, v1
	v_lshl_add_u64 v[26:27], s[6:7], 0, v[186:187]
	s_mov_b64 s[6:7], 0
	s_branch .LBB0_816

; __device__ __forceinline__ unsigned xb_add(unsigned* p, unsigned v) { return __hip_atomic_fetch_add(p, v, __ATOMIC_RELAXED, __HIP_MEMORY_SCOPE_AGENT); }
; __device__ __forceinline__ void xcd_barrier(const XcdBarrier& b) {
;     asm volatile("s_waitcnt vmcnt(0)" ::: "memory");
;     __syncthreads();
;     if (threadIdx.x == 0) {
;         unsigned* bar = b.bar;
;         __builtin_amdgcn_s_waitcnt(0);
;         unsigned nloc = b.st[0], nx = b.st[1];
;         if (nloc == 0u) { xcd_barrier_complete(bar, b.x, nloc, nx); b.st[0] = nloc; b.st[1] = nx; }
;         const unsigned old = xb_add(&bar[XB_XSUB(b.x)], 1u);
.LBB0_819:
	s_or_b64 exec, exec, s[4:5]
	s_waitcnt vmcnt(0)
	s_waitcnt lgkmcnt(0)
	s_barrier
	s_add_i32 s98, s98, 1
	s_mov_b64 s[0:1], exec
	v_readlane_b32 s4, v252, 0
	v_readlane_b32 s5, v252, 1
	s_and_b64 s[4:5], s[0:1], s[4:5]
	s_mov_b64 exec, s[4:5]
	s_cbranch_execz .LBB0_142
	s_add_u32 s10, s88, 0x9000
	s_addc_u32 s11, s89, 0
	s_cmp_lg_u32 s100, 0
	s_cbranch_scc1 .Lxb_have_w
	s_add_u32 s8, s88, 0x1400
	s_addc_u32 s9, s89, 0
